# grid barrier: non-last arrivers poll the global generation word directly (one poll hop less per barrier)
# speedup vs baseline: 1.0763x; 1.0048x over previous
; DI unsigned xb_ld(unsigned* p) { return __hip_atomic_load(p, __ATOMIC_RELAXED, __HIP_MEMORY_SCOPE_AGENT); }
; DI unsigned xb_add(unsigned* p, unsigned v) { return __hip_atomic_fetch_add(p, v, __ATOMIC_RELAXED, __HIP_MEMORY_SCOPE_AGENT); }
; #define XB_SPIN(cond, bar) do { unsigned _sp = 0; while (cond) { __builtin_amdgcn_s_sleep(2); \
;     if ((++_sp & 255u) == 0u) { if (xb_ld(&(bar)[XB_TMO])) break; if (_sp > XB_SPIN_CAP) { atomicAdd(&(bar)[XB_TMO], 1u); break; } } } } while (0)
; DI void xcd_barrier(const XcdBarrier& b) {
;     ...
;         const unsigned old = xb_add(&bar[XB_XSUB(b.x)], 1u);
;         const unsigned gen = old / nloc;
;         if (old + 1u == (gen + 1u) * nloc) {
;             __builtin_amdgcn_fence(__ATOMIC_RELEASE, "agent");
;             asm volatile("s_waitcnt vmcnt(0)" ::: "memory");
;             const unsigned og = xb_add(&bar[XB_TOP], 1u);
;             const unsigned tg = og / nx;
;             if (og + 1u == (tg + 1u) * nx) xb_add(&bar[XB_TOPGEN], 1u);
;             else XB_SPIN(xb_ld(&bar[XB_TOPGEN]) == tg, bar);
;             __builtin_amdgcn_fence(__ATOMIC_ACQUIRE, "agent");
;             xb_add(&bar[XB_XGEN(b.x)], 1u);
;             asm volatile("s_waitcnt vmcnt(0)" ::: "memory");
;         } else {
;             XB_SPIN(xb_ld(&bar[XB_XGEN(b.x)]) == gen, bar);
;             __builtin_amdgcn_fence(__ATOMIC_ACQUIRE, "agent");
;             asm volatile("s_waitcnt vmcnt(0)" ::: "memory");
;         }
.Lbw_0_0:
	v_sub_u32_e32 v5, 0, v4
	v_rcp_iflag_f32_e32 v6, v6
	v_add_u32_e32 v7, s6, v3
	v_mul_f32_e32 v6, 0x4f7ffffe, v6
	v_cvt_u32_f32_e32 v6, v6
	v_mul_lo_u32 v3, v5, v6
	v_mul_hi_u32 v3, v6, v3
	v_add_u32_e32 v3, v6, v3
	v_mul_hi_u32 v3, v7, v3
	v_mul_lo_u32 v5, v3, v4
	v_sub_u32_e32 v5, v7, v5
	v_add_u32_e32 v6, 1, v3
	v_cmp_ge_u32_e32 vcc, v5, v4
	s_nop 1
	v_cndmask_b32_e32 v3, v3, v6, vcc
	v_sub_u32_e32 v6, v5, v4
	v_cndmask_b32_e32 v5, v5, v6, vcc
	v_add_u32_e32 v6, 1, v3
	v_cmp_ge_u32_e32 vcc, v5, v4
	v_add_u32_e32 v5, 1, v7
	s_nop 0
	v_cndmask_b32_e32 v3, v3, v6, vcc
	v_mul_lo_u32 v6, v4, v3
	v_add_u32_e32 v4, v6, v4
	v_cmp_ne_u32_e32 vcc, v5, v4
	s_and_saveexec_b64 s[6:7], vcc
	s_xor_b64 s[10:11], exec, s[6:7]
	s_cbranch_execz .LBB0_74
	s_waitcnt lgkmcnt(0)
	s_add_u32 s16, s54, 0xfc17d00
	s_addc_u32 s17, s55, 0
	v_mov_b32_e32 v2, 0
	global_load_dword v2, v2, s[16:17] sc1
	s_waitcnt vmcnt(0)
	v_cmp_eq_u32_e32 vcc, v2, v3
	s_and_saveexec_b64 s[12:13], vcc
	s_cbranch_execz .LBB0_73
	s_add_u32 s14, s54, 0xfc14a00
	s_addc_u32 s15, s55, 0
	s_mov_b32 s6, 1
	s_mov_b64 s[18:19], 0
	v_mov_b32_e32 v2, 0
	s_branch .LBB0_64

; DI unsigned xb_ld(unsigned* p) { return __hip_atomic_load(p, __ATOMIC_RELAXED, __HIP_MEMORY_SCOPE_AGENT); }
; DI unsigned xb_add(unsigned* p, unsigned v) { return __hip_atomic_fetch_add(p, v, __ATOMIC_RELAXED, __HIP_MEMORY_SCOPE_AGENT); }
; #define XB_SPIN(cond, bar) do { unsigned _sp = 0; while (cond) { __builtin_amdgcn_s_sleep(2); \
;     if ((++_sp & 255u) == 0u) { if (xb_ld(&(bar)[XB_TMO])) break; if (_sp > XB_SPIN_CAP) { atomicAdd(&(bar)[XB_TMO], 1u); break; } } } } while (0)
; DI void xcd_barrier(const XcdBarrier& b) {
;     ...
;         const unsigned old = xb_add(&bar[XB_XSUB(b.x)], 1u);
;         const unsigned gen = old / nloc;
;         if (old + 1u == (gen + 1u) * nloc) {
;             __builtin_amdgcn_fence(__ATOMIC_RELEASE, "agent");
;             asm volatile("s_waitcnt vmcnt(0)" ::: "memory");
;             const unsigned og = xb_add(&bar[XB_TOP], 1u);
;             const unsigned tg = og / nx;
;             if (og + 1u == (tg + 1u) * nx) xb_add(&bar[XB_TOPGEN], 1u);
;             else XB_SPIN(xb_ld(&bar[XB_TOPGEN]) == tg, bar);
;             __builtin_amdgcn_fence(__ATOMIC_ACQUIRE, "agent");
;             xb_add(&bar[XB_XGEN(b.x)], 1u);
;             asm volatile("s_waitcnt vmcnt(0)" ::: "memory");
;         } else {
;             XB_SPIN(xb_ld(&bar[XB_XGEN(b.x)]) == gen, bar);
;             __builtin_amdgcn_fence(__ATOMIC_ACQUIRE, "agent");
;             asm volatile("s_waitcnt vmcnt(0)" ::: "memory");
;         }
.Lbw_1_0:
	v_sub_u32_e32 v5, 0, v4
	v_rcp_iflag_f32_e32 v6, v6
	v_add_u32_e32 v7, s2, v3
	v_mul_f32_e32 v6, 0x4f7ffffe, v6
	v_cvt_u32_f32_e32 v6, v6
	v_mul_lo_u32 v3, v5, v6
	v_mul_hi_u32 v3, v6, v3
	v_add_u32_e32 v3, v6, v3
	v_mul_hi_u32 v3, v7, v3
	v_mul_lo_u32 v5, v3, v4
	v_sub_u32_e32 v5, v7, v5
	v_add_u32_e32 v6, 1, v3
	v_cmp_ge_u32_e32 vcc, v5, v4
	s_nop 1
	v_cndmask_b32_e32 v3, v3, v6, vcc
	v_sub_u32_e32 v6, v5, v4
	v_cndmask_b32_e32 v5, v5, v6, vcc
	v_add_u32_e32 v6, 1, v3
	v_cmp_ge_u32_e32 vcc, v5, v4
	v_add_u32_e32 v5, 1, v7
	s_nop 0
	v_cndmask_b32_e32 v3, v3, v6, vcc
	v_mul_lo_u32 v6, v4, v3
	v_add_u32_e32 v4, v6, v4
	v_cmp_ne_u32_e32 vcc, v5, v4
	s_and_saveexec_b64 s[2:3], vcc
	s_xor_b64 s[6:7], exec, s[2:3]
	s_cbranch_execz .LBB0_176
	s_waitcnt lgkmcnt(0)
	s_add_u32 s12, s54, 0xfc17d00
	s_addc_u32 s13, s55, 0
	v_mov_b32_e32 v2, 0
	global_load_dword v2, v2, s[12:13] sc1
	s_waitcnt vmcnt(0)
	v_cmp_eq_u32_e32 vcc, v2, v3
	s_and_saveexec_b64 s[8:9], vcc
	s_cbranch_execz .LBB0_175
	s_add_u32 s10, s54, 0xfc14a00
	s_addc_u32 s11, s55, 0
	s_mov_b32 s2, 1
	s_mov_b64 s[14:15], 0
	v_mov_b32_e32 v2, 0
	s_branch .LBB0_166

; DI unsigned xb_ld(unsigned* p) { return __hip_atomic_load(p, __ATOMIC_RELAXED, __HIP_MEMORY_SCOPE_AGENT); }
; DI unsigned xb_add(unsigned* p, unsigned v) { return __hip_atomic_fetch_add(p, v, __ATOMIC_RELAXED, __HIP_MEMORY_SCOPE_AGENT); }
; #define XB_SPIN(cond, bar) do { unsigned _sp = 0; while (cond) { __builtin_amdgcn_s_sleep(2); \
;     if ((++_sp & 255u) == 0u) { if (xb_ld(&(bar)[XB_TMO])) break; if (_sp > XB_SPIN_CAP) { atomicAdd(&(bar)[XB_TMO], 1u); break; } } } } while (0)
; DI void xcd_barrier(const XcdBarrier& b) {
;     ...
;         const unsigned old = xb_add(&bar[XB_XSUB(b.x)], 1u);
;         const unsigned gen = old / nloc;
;         if (old + 1u == (gen + 1u) * nloc) {
;             __builtin_amdgcn_fence(__ATOMIC_RELEASE, "agent");
;             asm volatile("s_waitcnt vmcnt(0)" ::: "memory");
;             const unsigned og = xb_add(&bar[XB_TOP], 1u);
;             const unsigned tg = og / nx;
;             if (og + 1u == (tg + 1u) * nx) xb_add(&bar[XB_TOPGEN], 1u);
;             else XB_SPIN(xb_ld(&bar[XB_TOPGEN]) == tg, bar);
;             __builtin_amdgcn_fence(__ATOMIC_ACQUIRE, "agent");
;             xb_add(&bar[XB_XGEN(b.x)], 1u);
;             asm volatile("s_waitcnt vmcnt(0)" ::: "memory");
;         } else {
;             XB_SPIN(xb_ld(&bar[XB_XGEN(b.x)]) == gen, bar);
;             __builtin_amdgcn_fence(__ATOMIC_ACQUIRE, "agent");
;             asm volatile("s_waitcnt vmcnt(0)" ::: "memory");
;         }
.Lbw_4_0:
	v_sub_u32_e32 v4, 0, v3
	v_rcp_iflag_f32_e32 v5, v5
	v_add_u32_e32 v6, s4, v2
	v_mul_f32_e32 v5, 0x4f7ffffe, v5
	v_cvt_u32_f32_e32 v5, v5
	v_mul_lo_u32 v2, v4, v5
	v_mul_hi_u32 v2, v5, v2
	v_add_u32_e32 v2, v5, v2
	v_mul_hi_u32 v2, v6, v2
	v_mul_lo_u32 v4, v2, v3
	v_sub_u32_e32 v4, v6, v4
	v_add_u32_e32 v5, 1, v2
	v_cmp_ge_u32_e32 vcc, v4, v3
	s_nop 1
	v_cndmask_b32_e32 v2, v2, v5, vcc
	v_sub_u32_e32 v5, v4, v3
	v_cndmask_b32_e32 v4, v4, v5, vcc
	v_add_u32_e32 v5, 1, v2
	v_cmp_ge_u32_e32 vcc, v4, v3
	v_add_u32_e32 v4, 1, v6
	s_nop 0
	v_cndmask_b32_e32 v2, v2, v5, vcc
	v_mul_lo_u32 v5, v3, v2
	v_add_u32_e32 v3, v5, v3
	v_cmp_ne_u32_e32 vcc, v4, v3
	s_and_saveexec_b64 s[4:5], vcc
	s_xor_b64 s[4:5], exec, s[4:5]
	s_cbranch_execz .LBB0_555
	s_waitcnt lgkmcnt(0)
	s_add_u32 s10, s54, 0xfc17d00
	s_addc_u32 s11, s55, 0
	v_mov_b32_e32 v1, 0
	global_load_dword v1, v1, s[10:11] sc1
	s_waitcnt vmcnt(0)
	v_cmp_eq_u32_e32 vcc, v1, v2
	s_and_saveexec_b64 s[6:7], vcc
	s_cbranch_execz .LBB0_554
	s_add_u32 s8, s54, 0xfc14a00
	s_addc_u32 s9, s55, 0
	s_mov_b32 s22, 1
	s_mov_b64 s[12:13], 0
	v_mov_b32_e32 v1, 0
	s_branch .LBB0_545
